# baseline (speedup 1.0000x reference)
; #define SCHED() __builtin_amdgcn_sched_barrier(0)
; #define LGKM(n) asm volatile("s_waitcnt lgkmcnt(%0)" ::"n"(n) : "memory")
; #define STAGE_A(b, h, kt) STAGE_AX(Ag, b, h, kt)
; #define STAGE_B(b, h, kt) STAGE_BX(Bg, b, h, kt)
; #define LDA(b, h) do { const unsigned pa_ = lds0 + SLOTA(b, h) + wr * 8192 + laneoff; _Pragma("unroll") for (int m = 0; m < 4; ++m)   \
;       _Pragma("unroll") for (int k = 0; k < 2; ++k) DSR(At[m][k], pa_, m * 2048 + k * 1024); } while (0)
; #define LDB(dst, b, h) do { const unsigned pb_ = lds0 + SLOTB(b, h) + wc * 4096 + laneoff; _Pragma("unroll") for (int n = 0; n < 2; ++n) \
;       _Pragma("unroll") for (int k = 0; k < 2; ++k) DSR(dst[n][k], pb_, n * 2048 + k * 1024); } while (0)
; #define BAR __builtin_amdgcn_s_barrier()
; #define LGKM(n) asm volatile("s_waitcnt lgkmcnt(%0)" ::"n"(n) : "memory")
; template <int EPI, bool SWP> ...
;     ...
;     LDB(B0, 0, 0); LDA(0, 0); STAGE_A(1, 1, t + 1);
;     LGKM(8); BAR; LGKM(0); SCHED(); MMA(0, 0, B0); BAR; SCHED();
;     LDB(B1, 0, 1); STAGE_B(0, 0, t + 2);
;     BAR; LGKM(0); SCHED(); MMA(0, 1, B1); BAR; SCHED();
;     LDA(0, 1); STAGE_A(0, 0, t + 2);
;     BAR; LGKM(0); SCHED(); MMA(1, 0, B0); BAR; SCHED();
.LBB0_81:
	ds_read_b128 v[128:131], v219 offset:0
	ds_read_b128 v[132:135], v219 offset:0x400
	ds_read_b128 v[136:139], v219 offset:0x800
	ds_read_b128 v[140:143], v219 offset:0xc00
	ds_read_b128 v[144:147], v220 offset:0
	ds_read_b128 v[148:151], v220 offset:0x400
	ds_read_b128 v[152:155], v220 offset:0x800
	ds_read_b128 v[156:159], v220 offset:0xc00
	ds_read_b128 v[160:163], v220 offset:0x1000
	ds_read_b128 v[164:167], v220 offset:0x1400
	ds_read_b128 v[168:171], v220 offset:0x1800
	v_lshl_add_u64 v[192:193], s[76:77], 0, v[210:211]
	s_mov_b32 m0, s79
	ds_read_b128 v[172:175], v220 offset:0x1c00
	s_add_u32 s94, s76, s44
	s_addc_u32 s95, s77, s45
	global_load_lds_dwordx4 v210, s[94:95]
	s_mov_b32 m0, s80
	s_nop 0
	s_add_u32 s94, s76, s48
	s_addc_u32 s95, s77, s49
	global_load_lds_dwordx4 v210, s[94:95]
	s_waitcnt lgkmcnt(8)
	s_barrier
	s_waitcnt lgkmcnt(0)
	v_mfma_f32_16x16x32_bf16 v[124:127], v[128:131], v[144:147], v[124:127]
	v_mfma_f32_16x16x32_bf16 v[120:123], v[136:139], v[144:147], v[120:123]
	v_mfma_f32_16x16x32_bf16 v[116:119], v[128:131], v[152:155], v[116:119]
	v_mfma_f32_16x16x32_bf16 v[112:115], v[136:139], v[152:155], v[112:115]
	v_mfma_f32_16x16x32_bf16 v[108:111], v[128:131], v[160:163], v[108:111]
	v_mfma_f32_16x16x32_bf16 v[104:107], v[136:139], v[160:163], v[104:107]
	v_mfma_f32_16x16x32_bf16 v[100:103], v[128:131], v[168:171], v[100:103]
	v_mfma_f32_16x16x32_bf16 v[96:99], v[136:139], v[168:171], v[96:99]
	v_mfma_f32_16x16x32_bf16 v[124:127], v[132:135], v[148:151], v[124:127]
	v_mfma_f32_16x16x32_bf16 v[120:123], v[140:143], v[148:151], v[120:123]
	v_mfma_f32_16x16x32_bf16 v[116:119], v[132:135], v[156:159], v[116:119]
	v_mfma_f32_16x16x32_bf16 v[112:115], v[140:143], v[156:159], v[112:115]
	v_mfma_f32_16x16x32_bf16 v[108:111], v[132:135], v[164:167], v[108:111]
	v_mfma_f32_16x16x32_bf16 v[104:107], v[140:143], v[164:167], v[104:107]
	v_mfma_f32_16x16x32_bf16 v[100:103], v[132:135], v[172:175], v[100:103]
	v_mfma_f32_16x16x32_bf16 v[96:99], v[140:143], v[172:175], v[96:99]
	s_barrier
	ds_read_b128 v[176:179], v221 offset:0
	ds_read_b128 v[180:183], v221 offset:0x400
	ds_read_b128 v[184:187], v221 offset:0x800
	v_lshl_add_u64 v[194:195], s[74:75], 0, v[210:211]
	s_mov_b64 s[84:85], 0x30100100
	s_mov_b32 m0, s19
	ds_read_b128 v[188:191], v221 offset:0xc00
	s_mov_b64 s[84:85], 0x30140100
	s_add_u32 s94, s74, 0x30100100
	s_addc_u32 s95, s75, 0
	global_load_lds_dwordx4 v210, s[94:95]
	s_mov_b32 m0, s30
	s_nop 0
	s_add_u32 s94, s74, 0x30140100
	s_addc_u32 s95, s75, 0
	global_load_lds_dwordx4 v210, s[94:95]
	s_barrier
	s_waitcnt lgkmcnt(0)
	v_mfma_f32_16x16x32_bf16 v[92:95], v[176:179], v[144:147], v[92:95]
	v_mfma_f32_16x16x32_bf16 v[88:91], v[184:187], v[144:147], v[88:91]
	v_mfma_f32_16x16x32_bf16 v[84:87], v[176:179], v[152:155], v[84:87]
	v_mfma_f32_16x16x32_bf16 v[80:83], v[184:187], v[152:155], v[80:83]
	v_mfma_f32_16x16x32_bf16 v[76:79], v[176:179], v[160:163], v[76:79]
	v_mfma_f32_16x16x32_bf16 v[72:75], v[184:187], v[160:163], v[72:75]
	v_mfma_f32_16x16x32_bf16 v[68:71], v[176:179], v[168:171], v[68:71]
	v_mfma_f32_16x16x32_bf16 v[64:67], v[184:187], v[168:171], v[64:67]
	v_mfma_f32_16x16x32_bf16 v[92:95], v[180:183], v[148:151], v[92:95]
	v_mfma_f32_16x16x32_bf16 v[88:91], v[188:191], v[148:151], v[88:91]
	v_mfma_f32_16x16x32_bf16 v[84:87], v[180:183], v[156:159], v[84:87]
	v_mfma_f32_16x16x32_bf16 v[80:83], v[188:191], v[156:159], v[80:83]
	v_mfma_f32_16x16x32_bf16 v[76:79], v[180:183], v[164:167], v[76:79]
	v_mfma_f32_16x16x32_bf16 v[72:75], v[188:191], v[164:167], v[72:75]
	v_mfma_f32_16x16x32_bf16 v[68:71], v[180:183], v[172:175], v[68:71]
	v_mfma_f32_16x16x32_bf16 v[64:67], v[188:191], v[172:175], v[64:67]
	s_barrier
	ds_read_b128 v[144:147], v222 offset:0
	ds_read_b128 v[148:151], v222 offset:0x400
	ds_read_b128 v[152:155], v222 offset:0x800
	ds_read_b128 v[156:159], v222 offset:0xc00
	ds_read_b128 v[160:163], v222 offset:0x1000
	ds_read_b128 v[164:167], v222 offset:0x1400
	ds_read_b128 v[168:171], v222 offset:0x1800
	s_mov_b64 s[84:85], 0x100
	s_mov_b32 m0, s3
	ds_read_b128 v[172:175], v222 offset:0x1c00
	s_mov_b64 s[84:85], 0x40100
	s_add_u32 s94, s76, 0x100
	s_addc_u32 s95, s77, 0
	global_load_lds_dwordx4 v210, s[94:95]
	s_mov_b32 m0, s31
	s_nop 0
	s_add_u32 s94, s76, 0x40100
	s_addc_u32 s95, s77, 0
	global_load_lds_dwordx4 v210, s[94:95]
	s_barrier
	s_waitcnt lgkmcnt(0)
	v_mfma_f32_16x16x32_bf16 v[60:63], v[128:131], v[144:147], v[60:63]
	v_mfma_f32_16x16x32_bf16 v[56:59], v[136:139], v[144:147], v[56:59]
	v_mfma_f32_16x16x32_bf16 v[52:55], v[128:131], v[152:155], v[52:55]
	v_mfma_f32_16x16x32_bf16 v[48:51], v[136:139], v[152:155], v[48:51]
	v_mfma_f32_16x16x32_bf16 v[44:47], v[128:131], v[160:163], v[44:47]
	v_mfma_f32_16x16x32_bf16 v[40:43], v[136:139], v[160:163], v[40:43]
	v_mfma_f32_16x16x32_bf16 v[36:39], v[128:131], v[168:171], v[36:39]
	v_mfma_f32_16x16x32_bf16 v[32:35], v[136:139], v[168:171], v[32:35]
	v_mfma_f32_16x16x32_bf16 v[60:63], v[132:135], v[148:151], v[60:63]
	v_mfma_f32_16x16x32_bf16 v[56:59], v[140:143], v[148:151], v[56:59]
	v_mfma_f32_16x16x32_bf16 v[52:55], v[132:135], v[156:159], v[52:55]
	v_mfma_f32_16x16x32_bf16 v[48:51], v[140:143], v[156:159], v[48:51]
	v_mfma_f32_16x16x32_bf16 v[44:47], v[132:135], v[164:167], v[44:47]
	v_mfma_f32_16x16x32_bf16 v[40:43], v[140:143], v[164:167], v[40:43]
	v_mfma_f32_16x16x32_bf16 v[36:39], v[132:135], v[172:175], v[36:39]
	v_mfma_f32_16x16x32_bf16 v[32:35], v[140:143], v[172:175], v[32:35]
	s_barrier
; #define WAIT_V(n) asm volatile("s_waitcnt vmcnt(%0)" ::"n"(n) : "memory")
; #define SCHED() __builtin_amdgcn_sched_barrier(0)
; #define LGKM(n) asm volatile("s_waitcnt lgkmcnt(%0)" ::"n"(n) : "memory")
; #define STAGE_A(b, h, kt) STAGE_AX(Ag, b, h, kt)
; #define STAGE_B(b, h, kt) STAGE_BX(Bg, b, h, kt)
; #define LDA(b, h) do { const unsigned pa_ = lds0 + SLOTA(b, h) + wr * 8192 + laneoff; _Pragma("unroll") for (int m = 0; m < 4; ++m)   \
;       _Pragma("unroll") for (int k = 0; k < 2; ++k) DSR(At[m][k], pa_, m * 2048 + k * 1024); } while (0)
; #define LDB(dst, b, h) do { const unsigned pb_ = lds0 + SLOTB(b, h) + wc * 4096 + laneoff; _Pragma("unroll") for (int n = 0; n < 2; ++n) \
;       _Pragma("unroll") for (int k = 0; k < 2; ++k) DSR(dst[n][k], pb_, n * 2048 + k * 1024); } while (0)
; #define BAR __builtin_amdgcn_s_barrier()
; #define LGKM(n) asm volatile("s_waitcnt lgkmcnt(%0)" ::"n"(n) : "memory")
; template <int EPI, bool SWP> ...
;     ...
;     STAGE_B(0, 1, t + 2);
;     WAIT_V(6); BAR; SCHED(); MMA(1, 1, B1); BAR; SCHED();
;     LDB(B0, 1, 0); LDA(1, 0); STAGE_A(0, 1, t + 2);
;     LGKM(8); BAR; LGKM(0); SCHED(); MMA(0, 0, B0); BAR; SCHED();
;     LDB(B1, 1, 1); STAGE_B(1, 0, t + 3);
;     BAR; LGKM(0); SCHED(); MMA(0, 1, B1); BAR; SCHED();
;     LDA(1, 1); STAGE_A(1, 0, t + 3);
	s_mov_b64 s[84:85], 0x30180100
	s_mov_b32 m0, s50
	s_mov_b64 s[84:85], 0x301c0100
	s_add_u32 s94, s74, 0x30180100
	s_addc_u32 s95, s75, 0
	global_load_lds_dwordx4 v210, s[94:95]
	s_mov_b32 m0, s51
	s_nop 0
	s_add_u32 s94, s74, 0x301c0100
	s_addc_u32 s95, s75, 0
	global_load_lds_dwordx4 v210, s[94:95]
	s_waitcnt vmcnt(6)
	s_barrier
	v_mfma_f32_16x16x32_bf16 v[28:31], v[176:179], v[144:147], v[28:31]
	v_mfma_f32_16x16x32_bf16 v[24:27], v[184:187], v[144:147], v[24:27]
	v_mfma_f32_16x16x32_bf16 v[20:23], v[176:179], v[152:155], v[20:23]
	v_mfma_f32_16x16x32_bf16 v[16:19], v[184:187], v[152:155], v[16:19]
	v_mfma_f32_16x16x32_bf16 v[12:15], v[176:179], v[160:163], v[12:15]
	v_mfma_f32_16x16x32_bf16 v[8:11], v[184:187], v[160:163], v[8:11]
	v_mfma_f32_16x16x32_bf16 v[4:7], v[176:179], v[168:171], v[4:7]
	v_mfma_f32_16x16x32_bf16 v[0:3], v[184:187], v[168:171], v[0:3]
	v_mfma_f32_16x16x32_bf16 v[28:31], v[180:183], v[148:151], v[28:31]
	v_mfma_f32_16x16x32_bf16 v[24:27], v[188:191], v[148:151], v[24:27]
	v_mfma_f32_16x16x32_bf16 v[20:23], v[180:183], v[156:159], v[20:23]
	v_mfma_f32_16x16x32_bf16 v[16:19], v[188:191], v[156:159], v[16:19]
	v_mfma_f32_16x16x32_bf16 v[12:15], v[180:183], v[164:167], v[12:15]
	v_mfma_f32_16x16x32_bf16 v[8:11], v[188:191], v[164:167], v[8:11]
	v_mfma_f32_16x16x32_bf16 v[4:7], v[180:183], v[172:175], v[4:7]
	v_mfma_f32_16x16x32_bf16 v[0:3], v[188:191], v[172:175], v[0:3]
	s_barrier
	ds_read_b128 v[128:131], v223 offset:0
	ds_read_b128 v[132:135], v223 offset:0x400
	ds_read_b128 v[136:139], v223 offset:0x800
	ds_read_b128 v[140:143], v223 offset:0xc00
	ds_read_b128 v[144:147], v224 offset:0
	ds_read_b128 v[148:151], v224 offset:0x400
	ds_read_b128 v[152:155], v224 offset:0x800
	ds_read_b128 v[156:159], v224 offset:0xc00
	ds_read_b128 v[160:163], v224 offset:0x1000
	ds_read_b128 v[164:167], v224 offset:0x1400
	ds_read_b128 v[168:171], v224 offset:0x1800
	s_mov_b64 s[84:85], 0x80100
	s_mov_b32 m0, s64
	ds_read_b128 v[172:175], v224 offset:0x1c00
	s_mov_b64 s[84:85], 0xc0100
	s_add_u32 s94, s76, 0x80100
	s_addc_u32 s95, s77, 0
	global_load_lds_dwordx4 v210, s[94:95]
	s_mov_b32 m0, s65
	s_nop 0
	s_add_u32 s94, s76, 0xc0100
	s_addc_u32 s95, s77, 0
	global_load_lds_dwordx4 v210, s[94:95]
	s_waitcnt lgkmcnt(8)
	s_barrier
	s_waitcnt lgkmcnt(0)
	v_mfma_f32_16x16x32_bf16 v[124:127], v[128:131], v[144:147], v[124:127]
	v_mfma_f32_16x16x32_bf16 v[120:123], v[136:139], v[144:147], v[120:123]
	v_mfma_f32_16x16x32_bf16 v[116:119], v[128:131], v[152:155], v[116:119]
	v_mfma_f32_16x16x32_bf16 v[112:115], v[136:139], v[152:155], v[112:115]
	v_mfma_f32_16x16x32_bf16 v[108:111], v[128:131], v[160:163], v[108:111]
	v_mfma_f32_16x16x32_bf16 v[104:107], v[136:139], v[160:163], v[104:107]
	v_mfma_f32_16x16x32_bf16 v[100:103], v[128:131], v[168:171], v[100:103]
	v_mfma_f32_16x16x32_bf16 v[96:99], v[136:139], v[168:171], v[96:99]
	v_mfma_f32_16x16x32_bf16 v[124:127], v[132:135], v[148:151], v[124:127]
	v_mfma_f32_16x16x32_bf16 v[120:123], v[140:143], v[148:151], v[120:123]
	v_mfma_f32_16x16x32_bf16 v[116:119], v[132:135], v[156:159], v[116:119]
	v_mfma_f32_16x16x32_bf16 v[112:115], v[140:143], v[156:159], v[112:115]
	v_mfma_f32_16x16x32_bf16 v[108:111], v[132:135], v[164:167], v[108:111]
	v_mfma_f32_16x16x32_bf16 v[104:107], v[140:143], v[164:167], v[104:107]
	v_mfma_f32_16x16x32_bf16 v[100:103], v[132:135], v[172:175], v[100:103]
	v_mfma_f32_16x16x32_bf16 v[96:99], v[140:143], v[172:175], v[96:99]
	s_barrier
	ds_read_b128 v[176:179], v225 offset:0
	ds_read_b128 v[180:183], v225 offset:0x400
	ds_read_b128 v[184:187], v225 offset:0x800
	s_mov_b64 s[84:85], 0x30100180
	s_add_i32 s83, s3, 0x18000
	ds_read_b128 v[188:191], v225 offset:0xc00
	s_mov_b32 m0, s83
	s_mov_b64 s[84:85], 0x30140180
	s_add_u32 s94, s74, 0x30100180
	s_addc_u32 s95, s75, 0
	global_load_lds_dwordx4 v210, s[94:95]
	s_mov_b32 m0, s66
	s_nop 0
	s_add_u32 s94, s74, 0x30140180
	s_addc_u32 s95, s75, 0
	global_load_lds_dwordx4 v210, s[94:95]
	s_barrier
	s_waitcnt lgkmcnt(0)
	v_mfma_f32_16x16x32_bf16 v[92:95], v[176:179], v[144:147], v[92:95]
	v_mfma_f32_16x16x32_bf16 v[88:91], v[184:187], v[144:147], v[88:91]
	v_mfma_f32_16x16x32_bf16 v[84:87], v[176:179], v[152:155], v[84:87]
	v_mfma_f32_16x16x32_bf16 v[80:83], v[184:187], v[152:155], v[80:83]
	v_mfma_f32_16x16x32_bf16 v[76:79], v[176:179], v[160:163], v[76:79]
	v_mfma_f32_16x16x32_bf16 v[72:75], v[184:187], v[160:163], v[72:75]
	v_mfma_f32_16x16x32_bf16 v[68:71], v[176:179], v[168:171], v[68:71]
	v_mfma_f32_16x16x32_bf16 v[64:67], v[184:187], v[168:171], v[64:67]
	v_mfma_f32_16x16x32_bf16 v[92:95], v[180:183], v[148:151], v[92:95]
	v_mfma_f32_16x16x32_bf16 v[88:91], v[188:191], v[148:151], v[88:91]
	v_mfma_f32_16x16x32_bf16 v[84:87], v[180:183], v[156:159], v[84:87]
	v_mfma_f32_16x16x32_bf16 v[80:83], v[188:191], v[156:159], v[80:83]
	v_mfma_f32_16x16x32_bf16 v[76:79], v[180:183], v[164:167], v[76:79]
	v_mfma_f32_16x16x32_bf16 v[72:75], v[188:191], v[164:167], v[72:75]
	v_mfma_f32_16x16x32_bf16 v[68:71], v[180:183], v[172:175], v[68:71]
	v_mfma_f32_16x16x32_bf16 v[64:67], v[188:191], v[172:175], v[64:67]
	s_barrier
	ds_read_b128 v[144:147], v226 offset:0
	ds_read_b128 v[148:151], v226 offset:0x400
	ds_read_b128 v[152:155], v226 offset:0x800
	ds_read_b128 v[156:159], v226 offset:0xc00
	ds_read_b128 v[160:163], v226 offset:0x1000
	ds_read_b128 v[164:167], v226 offset:0x1400
	s_mov_b64 s[84:85], 0x180
	ds_read_b128 v[168:171], v226 offset:0x1800
	s_add_i32 s84, s3, 0x8000
	ds_read_b128 v[172:175], v226 offset:0x1c00
	s_mov_b32 m0, s84
	s_mov_b64 s[86:87], 0x40180
	s_add_u32 s94, s76, 0x180
	s_addc_u32 s95, s77, 0
	global_load_lds_dwordx4 v210, s[94:95]
	v_lshl_add_u64 v[192:193], v[192:193], 0, s[86:87]
	s_mov_b32 m0, s67
	s_nop 0
	s_add_u32 s94, s76, 0x40180
	s_addc_u32 s95, s77, 0
	global_load_lds_dwordx4 v210, s[94:95]
	s_barrier
; #define WAIT_V(n) asm volatile("s_waitcnt vmcnt(%0)" ::"n"(n) : "memory")
; #define SCHED() __builtin_amdgcn_sched_barrier(0)
; #define LGKM(n) asm volatile("s_waitcnt lgkmcnt(%0)" ::"n"(n) : "memory")
; #define STAGE_A(b, h, kt) STAGE_AX(Ag, b, h, kt)
; #define STAGE_B(b, h, kt) STAGE_BX(Bg, b, h, kt)
; #define LDA(b, h) do { const unsigned pa_ = lds0 + SLOTA(b, h) + wr * 8192 + laneoff; _Pragma("unroll") for (int m = 0; m < 4; ++m)   \
;       _Pragma("unroll") for (int k = 0; k < 2; ++k) DSR(At[m][k], pa_, m * 2048 + k * 1024); } while (0)
; #define LDB(dst, b, h) do { const unsigned pb_ = lds0 + SLOTB(b, h) + wc * 4096 + laneoff; _Pragma("unroll") for (int n = 0; n < 2; ++n) \
;       _Pragma("unroll") for (int k = 0; k < 2; ++k) DSR(dst[n][k], pb_, n * 2048 + k * 1024); } while (0)
; #define BAR __builtin_amdgcn_s_barrier()
; #define LGKM(n) asm volatile("s_waitcnt lgkmcnt(%0)" ::"n"(n) : "memory")
; template <int EPI, bool SWP> ...
;     ...
;     BAR; LGKM(0); SCHED(); MMA(1, 0, B0); BAR; SCHED();
;     STAGE_B(1, 1, t + 3);
;     WAIT_V(6); BAR; SCHED(); MMA(1, 1, B1); BAR; SCHED();
;   }
;   { LDB(B0, 0, 0); LDA(0, 0); STAGE_A(1, 1, nt - 1);
;     BAR; LGKM(0); SCHED(); MMA(0, 0, B0); BAR; SCHED();
;     LDB(B1, 0, 1); BAR; LGKM(0); SCHED(); MMA(0, 1, B1); BAR; SCHED();
	s_waitcnt lgkmcnt(0)
	v_mfma_f32_16x16x32_bf16 v[60:63], v[128:131], v[144:147], v[60:63]
	v_mfma_f32_16x16x32_bf16 v[56:59], v[136:139], v[144:147], v[56:59]
	v_mfma_f32_16x16x32_bf16 v[52:55], v[128:131], v[152:155], v[52:55]
	v_mfma_f32_16x16x32_bf16 v[48:51], v[136:139], v[152:155], v[48:51]
	v_mfma_f32_16x16x32_bf16 v[44:47], v[128:131], v[160:163], v[44:47]
	v_mfma_f32_16x16x32_bf16 v[40:43], v[136:139], v[160:163], v[40:43]
	v_mfma_f32_16x16x32_bf16 v[36:39], v[128:131], v[168:171], v[36:39]
	v_mfma_f32_16x16x32_bf16 v[32:35], v[136:139], v[168:171], v[32:35]
	v_mfma_f32_16x16x32_bf16 v[60:63], v[132:135], v[148:151], v[60:63]
	v_mfma_f32_16x16x32_bf16 v[56:59], v[140:143], v[148:151], v[56:59]
	v_mfma_f32_16x16x32_bf16 v[52:55], v[132:135], v[156:159], v[52:55]
	v_mfma_f32_16x16x32_bf16 v[48:51], v[140:143], v[156:159], v[48:51]
	v_mfma_f32_16x16x32_bf16 v[44:47], v[132:135], v[164:167], v[44:47]
	v_mfma_f32_16x16x32_bf16 v[40:43], v[140:143], v[164:167], v[40:43]
	v_mfma_f32_16x16x32_bf16 v[36:39], v[132:135], v[172:175], v[36:39]
	v_mfma_f32_16x16x32_bf16 v[32:35], v[140:143], v[172:175], v[32:35]
	s_barrier
	s_mov_b64 s[86:87], 0x30180180
	s_add_i32 s85, s3, 0x1c000
	s_mov_b32 m0, s85
	s_mov_b64 s[86:87], 0x301c0180
	s_add_u32 s94, s74, 0x30180180
	s_addc_u32 s95, s75, 0
	global_load_lds_dwordx4 v210, s[94:95]
	s_mov_b32 m0, s78
	s_nop 0
	s_add_u32 s94, s74, 0x301c0180
	s_addc_u32 s95, s75, 0
	global_load_lds_dwordx4 v210, s[94:95]
	s_waitcnt vmcnt(6)
	s_barrier
	v_mfma_f32_16x16x32_bf16 v[28:31], v[176:179], v[144:147], v[28:31]
	v_mfma_f32_16x16x32_bf16 v[24:27], v[184:187], v[144:147], v[24:27]
	v_mfma_f32_16x16x32_bf16 v[20:23], v[176:179], v[152:155], v[20:23]
	v_mfma_f32_16x16x32_bf16 v[16:19], v[184:187], v[152:155], v[16:19]
	v_mfma_f32_16x16x32_bf16 v[12:15], v[176:179], v[160:163], v[12:15]
	v_mfma_f32_16x16x32_bf16 v[8:11], v[184:187], v[160:163], v[8:11]
	v_mfma_f32_16x16x32_bf16 v[4:7], v[176:179], v[168:171], v[4:7]
	v_mfma_f32_16x16x32_bf16 v[0:3], v[184:187], v[168:171], v[0:3]
	v_mfma_f32_16x16x32_bf16 v[28:31], v[180:183], v[148:151], v[28:31]
	v_mfma_f32_16x16x32_bf16 v[24:27], v[188:191], v[148:151], v[24:27]
	v_mfma_f32_16x16x32_bf16 v[20:23], v[180:183], v[156:159], v[20:23]
	v_mfma_f32_16x16x32_bf16 v[16:19], v[188:191], v[156:159], v[16:19]
	v_mfma_f32_16x16x32_bf16 v[12:15], v[180:183], v[164:167], v[12:15]
	v_mfma_f32_16x16x32_bf16 v[8:11], v[188:191], v[164:167], v[8:11]
	v_mfma_f32_16x16x32_bf16 v[4:7], v[180:183], v[172:175], v[4:7]
	v_mfma_f32_16x16x32_bf16 v[0:3], v[188:191], v[172:175], v[0:3]
	s_add_i32 s15, s15, 2
	s_add_u32 s74, s74, 0x100
	s_addc_u32 s75, s75, 0
	s_add_u32 s76, s76, 0x100
	s_addc_u32 s77, s77, 0
	s_cmp_gt_u32 s15, 27
	s_barrier
	s_cbranch_scc0 .LBB0_81
	ds_read_b128 v[136:139], v219 offset:0
	ds_read_b128 v[140:143], v219 offset:0x400
	ds_read_b128 v[144:147], v219 offset:0x800
	ds_read_b128 v[148:151], v219 offset:0xc00
	ds_read_b128 v[128:131], v220 offset:0
	ds_read_b128 v[132:135], v220 offset:0x400
	ds_read_b128 v[152:155], v220 offset:0x800
	ds_read_b128 v[156:159], v220 offset:0xc00
	ds_read_b128 v[160:163], v220 offset:0x1000
	ds_read_b128 v[164:167], v220 offset:0x1400
	v_lshl_add_u64 v[176:177], s[72:73], 0, v[208:209]
	ds_read_b128 v[168:171], v220 offset:0x1800
	s_mov_b64 s[72:73], 0x80f80
	s_mov_b32 m0, s79
	ds_read_b128 v[172:175], v220 offset:0x1c00
	v_lshl_add_u64 v[178:179], v[176:177], 0, s[72:73]
	s_mov_b64 s[72:73], 0xc0f80
	global_load_lds_dwordx4 v[178:179], off
	v_lshl_add_u64 v[176:177], v[176:177], 0, s[72:73]
	s_mov_b32 m0, s80
	s_ashr_i32 s15, s14, 31
	global_load_lds_dwordx4 v[176:177], off
	s_lshl_b64 s[72:73], s[14:15], 20
	s_add_u32 s72, s56, s72
	s_addc_u32 s73, s57, s73
	s_ashr_i32 s61, s60, 31
	s_barrier
	s_waitcnt lgkmcnt(0)
	s_lshl_b64 s[74:75], s[60:61], 20
	s_add_u32 s74, s10, s74
	s_addc_u32 s75, s11, s75
	v_mfma_f32_16x16x32_bf16 v[124:127], v[136:139], v[128:131], v[124:127]
	v_mfma_f32_16x16x32_bf16 v[120:123], v[144:147], v[128:131], v[120:123]
	v_mfma_f32_16x16x32_bf16 v[116:119], v[136:139], v[152:155], v[116:119]
	v_mfma_f32_16x16x32_bf16 v[112:115], v[144:147], v[152:155], v[112:115]
	v_mfma_f32_16x16x32_bf16 v[108:111], v[136:139], v[160:163], v[108:111]
	v_mfma_f32_16x16x32_bf16 v[104:107], v[144:147], v[160:163], v[104:107]
	v_mfma_f32_16x16x32_bf16 v[100:103], v[136:139], v[168:171], v[100:103]
	v_mfma_f32_16x16x32_bf16 v[96:99], v[144:147], v[168:171], v[96:99]
	v_mfma_f32_16x16x32_bf16 v[124:127], v[140:143], v[132:135], v[124:127]
	v_mfma_f32_16x16x32_bf16 v[120:123], v[148:151], v[132:135], v[120:123]
	v_mfma_f32_16x16x32_bf16 v[116:119], v[140:143], v[156:159], v[116:119]
	v_mfma_f32_16x16x32_bf16 v[112:115], v[148:151], v[156:159], v[112:115]
	v_mfma_f32_16x16x32_bf16 v[176:179], v[140:143], v[164:167], v[108:111]
	v_mfma_f32_16x16x32_bf16 v[180:183], v[148:151], v[164:167], v[104:107]
	v_mfma_f32_16x16x32_bf16 v[100:103], v[140:143], v[172:175], v[100:103]
	v_mfma_f32_16x16x32_bf16 v[96:99], v[148:151], v[172:175], v[96:99]
	s_barrier
	ds_read_b128 v[104:107], v221 offset:0
	ds_read_b128 v[108:111], v221 offset:0x400
	ds_read_b128 v[184:187], v221 offset:0x800
	ds_read_b128 v[188:191], v221 offset:0xc00
	s_barrier
; #define WAIT_V(n) asm volatile("s_waitcnt vmcnt(%0)" ::"n"(n) : "memory")
; #define SCHED() __builtin_amdgcn_sched_barrier(0)
; #define LGKM(n) asm volatile("s_waitcnt lgkmcnt(%0)" ::"n"(n) : "memory")
; #define LDA(b, h) do { const unsigned pa_ = lds0 + SLOTA(b, h) + wr * 8192 + laneoff; _Pragma("unroll") for (int m = 0; m < 4; ++m)   \
;       _Pragma("unroll") for (int k = 0; k < 2; ++k) DSR(At[m][k], pa_, m * 2048 + k * 1024); } while (0)
; #define LDB(dst, b, h) do { const unsigned pb_ = lds0 + SLOTB(b, h) + wc * 4096 + laneoff; _Pragma("unroll") for (int n = 0; n < 2; ++n) \
;       _Pragma("unroll") for (int k = 0; k < 2; ++k) DSR(dst[n][k], pb_, n * 2048 + k * 1024); } while (0)
; #define BAR __builtin_amdgcn_s_barrier()
; #define LGKM(n) asm volatile("s_waitcnt lgkmcnt(%0)" ::"n"(n) : "memory")
; template <int EPI, bool SWP> ...
;     ...
;     LDB(B1, 0, 1); BAR; LGKM(0); SCHED(); MMA(0, 1, B1); BAR; SCHED();
;     LDA(0, 1); WAIT_V(4); BAR; LGKM(0); SCHED(); MMA(1, 0, B0); MMA(1, 1, B1); BAR; SCHED(); }
;   { LDB(B0, 1, 0); LDA(1, 0); WAIT_V(2); BAR; LGKM(0); SCHED(); MMA(0, 0, B0); BAR; SCHED();
	s_waitcnt lgkmcnt(0)
	v_mfma_f32_16x16x32_bf16 v[92:95], v[104:107], v[128:131], v[92:95]
	v_mfma_f32_16x16x32_bf16 v[88:91], v[184:187], v[128:131], v[88:91]
	v_mfma_f32_16x16x32_bf16 v[84:87], v[104:107], v[152:155], v[84:87]
	v_mfma_f32_16x16x32_bf16 v[80:83], v[184:187], v[152:155], v[80:83]
	v_mfma_f32_16x16x32_bf16 v[76:79], v[104:107], v[160:163], v[76:79]
	v_mfma_f32_16x16x32_bf16 v[72:75], v[184:187], v[160:163], v[72:75]
	v_mfma_f32_16x16x32_bf16 v[68:71], v[104:107], v[168:171], v[68:71]
	v_mfma_f32_16x16x32_bf16 v[64:67], v[184:187], v[168:171], v[64:67]
	v_mfma_f32_16x16x32_bf16 v[192:195], v[108:111], v[132:135], v[92:95]
	v_mfma_f32_16x16x32_bf16 v[196:199], v[188:191], v[132:135], v[88:91]
	v_mfma_f32_16x16x32_bf16 v[84:87], v[108:111], v[156:159], v[84:87]
	v_mfma_f32_16x16x32_bf16 v[80:83], v[188:191], v[156:159], v[80:83]
	v_mfma_f32_16x16x32_bf16 v[200:203], v[108:111], v[164:167], v[76:79]
	v_mfma_f32_16x16x32_bf16 v[204:207], v[188:191], v[164:167], v[72:75]
	v_mfma_f32_16x16x32_bf16 v[68:71], v[108:111], v[172:175], v[68:71]
	v_mfma_f32_16x16x32_bf16 v[64:67], v[188:191], v[172:175], v[64:67]
	s_barrier
	ds_read_b128 v[72:75], v222 offset:0
	ds_read_b128 v[76:79], v222 offset:0x400
	ds_read_b128 v[88:91], v222 offset:0x800
	ds_read_b128 v[92:95], v222 offset:0xc00
	ds_read_b128 v[152:155], v222 offset:0x1000
	ds_read_b128 v[156:159], v222 offset:0x1400
	ds_read_b128 v[160:163], v222 offset:0x1800
	ds_read_b128 v[164:167], v222 offset:0x1c00
	s_waitcnt vmcnt(4)
	s_barrier
	s_waitcnt lgkmcnt(0)
	v_mfma_f32_16x16x32_bf16 v[60:63], v[136:139], v[72:75], v[60:63]
	v_mfma_f32_16x16x32_bf16 v[56:59], v[144:147], v[72:75], v[56:59]
	v_mfma_f32_16x16x32_bf16 v[52:55], v[136:139], v[88:91], v[52:55]
	v_mfma_f32_16x16x32_bf16 v[48:51], v[144:147], v[88:91], v[48:51]
	v_mfma_f32_16x16x32_bf16 v[44:47], v[136:139], v[152:155], v[44:47]
	v_mfma_f32_16x16x32_bf16 v[40:43], v[144:147], v[152:155], v[40:43]
	v_mfma_f32_16x16x32_bf16 v[36:39], v[136:139], v[160:163], v[36:39]
	v_mfma_f32_16x16x32_bf16 v[32:35], v[144:147], v[160:163], v[32:35]
	v_mfma_f32_16x16x32_bf16 v[60:63], v[140:143], v[76:79], v[60:63]
	v_mfma_f32_16x16x32_bf16 v[56:59], v[148:151], v[76:79], v[56:59]
	v_mfma_f32_16x16x32_bf16 v[52:55], v[140:143], v[92:95], v[52:55]
	v_mfma_f32_16x16x32_bf16 v[48:51], v[148:151], v[92:95], v[48:51]
	v_mfma_f32_16x16x32_bf16 v[128:131], v[140:143], v[156:159], v[44:47]
	v_mfma_f32_16x16x32_bf16 v[132:135], v[148:151], v[156:159], v[40:43]
	v_mfma_f32_16x16x32_bf16 v[36:39], v[140:143], v[164:167], v[36:39]
	v_mfma_f32_16x16x32_bf16 v[32:35], v[148:151], v[164:167], v[32:35]
	v_mfma_f32_16x16x32_bf16 v[28:31], v[104:107], v[72:75], v[28:31]
	v_mfma_f32_16x16x32_bf16 v[24:27], v[184:187], v[72:75], v[24:27]
	v_mfma_f32_16x16x32_bf16 v[20:23], v[104:107], v[88:91], v[20:23]
	v_mfma_f32_16x16x32_bf16 v[16:19], v[184:187], v[88:91], v[16:19]
	v_mfma_f32_16x16x32_bf16 v[12:15], v[104:107], v[152:155], v[12:15]
	v_mfma_f32_16x16x32_bf16 v[8:11], v[184:187], v[152:155], v[8:11]
	v_mfma_f32_16x16x32_bf16 v[4:7], v[104:107], v[160:163], v[4:7]
	v_mfma_f32_16x16x32_bf16 v[0:3], v[184:187], v[160:163], v[0:3]
	v_mfma_f32_16x16x32_bf16 v[136:139], v[108:111], v[76:79], v[28:31]
	v_mfma_f32_16x16x32_bf16 v[140:143], v[188:191], v[76:79], v[24:27]
	v_mfma_f32_16x16x32_bf16 v[20:23], v[108:111], v[92:95], v[20:23]
	v_mfma_f32_16x16x32_bf16 v[16:19], v[188:191], v[92:95], v[16:19]
	v_mfma_f32_16x16x32_bf16 v[144:147], v[108:111], v[156:159], v[12:15]
	v_mfma_f32_16x16x32_bf16 v[148:151], v[188:191], v[156:159], v[8:11]
	v_mfma_f32_16x16x32_bf16 v[4:7], v[108:111], v[164:167], v[4:7]
	v_mfma_f32_16x16x32_bf16 v[0:3], v[188:191], v[164:167], v[0:3]
	s_barrier
	ds_read_b128 v[8:11], v223 offset:0
	ds_read_b128 v[12:15], v223 offset:0x400
	ds_read_b128 v[152:155], v223 offset:0x800
	ds_read_b128 v[156:159], v223 offset:0xc00
	ds_read_b128 v[24:27], v224 offset:0
	ds_read_b128 v[28:31], v224 offset:0x400
	ds_read_b128 v[40:43], v224 offset:0x800
	ds_read_b128 v[44:47], v224 offset:0xc00
	ds_read_b128 v[184:187], v224 offset:0x1000
	ds_read_b128 v[188:191], v224 offset:0x1400
	ds_read_b128 v[212:215], v224 offset:0x1800
	ds_read_b128 v[236:239], v224 offset:0x1c00
	s_waitcnt vmcnt(2)
	s_barrier
; #define WAIT_V(n) asm volatile("s_waitcnt vmcnt(%0)" ::"n"(n) : "memory")
; #define SCHED() __builtin_amdgcn_sched_barrier(0)
; #define LGKM(n) asm volatile("s_waitcnt lgkmcnt(%0)" ::"n"(n) : "memory")
; #define STAGE_AX(AG, b, h, kt) do { _Pragma("unroll") for (int i = 0; i < 2; ++i)                                    \
;       __builtin_amdgcn_global_load_lds((const unsigned*)(((AG) + ((size_t)(kt) * (BK * 2) + (size_t)((h) * 2 + i) * 128 * lda)) + aoff), \
;                                        (unsigned*)(shm + SLOTA(b, h) + wid * 1024 + i * 8192), 16, 0, 0); } while (0)
; #define STAGE_BX(BG, b, h, kt) do { _Pragma("unroll") for (int i = 0; i < 2; ++i)                                    \
;       __builtin_amdgcn_global_load_lds((const unsigned*)(((BG) + ((size_t)(kt) * (BK * 2) + (size_t)((h) * 2 + i) * 128 * K)) + boff),   \
;                                        (unsigned*)(shm + SLOTB(b, h) + wid * 1024 + i * 8192), 16, 0, 0); } while (0)
; #define LDA(b, h) do { const unsigned pa_ = lds0 + SLOTA(b, h) + wr * 8192 + laneoff; _Pragma("unroll") for (int m = 0; m < 4; ++m)   \
;       _Pragma("unroll") for (int k = 0; k < 2; ++k) DSR(At[m][k], pa_, m * 2048 + k * 1024); } while (0)
; #define LDB(dst, b, h) do { const unsigned pb_ = lds0 + SLOTB(b, h) + wc * 4096 + laneoff; _Pragma("unroll") for (int n = 0; n < 2; ++n) \
;       _Pragma("unroll") for (int k = 0; k < 2; ++k) DSR(dst[n][k], pb_, n * 2048 + k * 1024); } while (0)
; #define BAR __builtin_amdgcn_s_barrier()
; #define LGKM(n) asm volatile("s_waitcnt lgkmcnt(%0)" ::"n"(n) : "memory")
; template <int EPI, bool SWP> ...
;     ...
;   { LDB(B0, 1, 0); LDA(1, 0); WAIT_V(2); BAR; LGKM(0); SCHED(); MMA(0, 0, B0); BAR; SCHED();
;     LDB(B1, 1, 1); WAIT_V(0); BAR; LGKM(0); SCHED(); MMA(0, 1, B1); BAR; SCHED();
;     LDA(1, 1);
;     if (has_next) { STAGE_BX(Bg_n, 0, 0, 0); STAGE_AX(Ag_n, 0, 0, 0); STAGE_BX(Bg_n, 0, 1, 0); STAGE_AX(Ag_n, 0, 1, 0); }
	s_waitcnt lgkmcnt(0)
	v_mfma_f32_16x16x32_bf16 v[72:75], v[8:11], v[24:27], v[124:127]
	v_mfma_f32_16x16x32_bf16 v[124:127], v[12:15], v[28:31], v[72:75]
	v_mfma_f32_16x16x32_bf16 v[72:75], v[152:155], v[24:27], v[120:123]
	v_mfma_f32_16x16x32_bf16 v[120:123], v[156:159], v[28:31], v[72:75]
	v_mfma_f32_16x16x32_bf16 v[72:75], v[8:11], v[40:43], v[116:119]
	v_mfma_f32_16x16x32_bf16 v[108:111], v[12:15], v[44:47], v[72:75]
	v_mfma_f32_16x16x32_bf16 v[72:75], v[152:155], v[40:43], v[112:115]
	v_mfma_f32_16x16x32_bf16 v[104:107], v[156:159], v[44:47], v[72:75]
	v_mfma_f32_16x16x32_bf16 v[72:75], v[8:11], v[184:187], v[176:179]
	v_mfma_f32_16x16x32_bf16 v[92:95], v[12:15], v[188:191], v[72:75]
	v_mfma_f32_16x16x32_bf16 v[72:75], v[152:155], v[184:187], v[180:183]
	v_mfma_f32_16x16x32_bf16 v[88:91], v[156:159], v[188:191], v[72:75]
	v_mfma_f32_16x16x32_bf16 v[72:75], v[8:11], v[212:215], v[100:103]
	v_mfma_f32_16x16x32_bf16 v[76:79], v[12:15], v[236:239], v[72:75]
	v_mfma_f32_16x16x32_bf16 v[72:75], v[152:155], v[212:215], v[96:99]
	v_mfma_f32_16x16x32_bf16 v[72:75], v[156:159], v[236:239], v[72:75]
	s_barrier
	ds_read_b128 v[160:163], v225 offset:0
	ds_read_b128 v[164:167], v225 offset:0x400
	ds_read_b128 v[168:171], v225 offset:0x800
	ds_read_b128 v[172:175], v225 offset:0xc00
	s_waitcnt vmcnt(0)
	s_barrier
	s_waitcnt lgkmcnt(0)
	v_mfma_f32_16x16x32_bf16 v[96:99], v[160:163], v[24:27], v[192:195]
	v_mfma_f32_16x16x32_bf16 v[24:27], v[168:171], v[24:27], v[196:199]
	v_mfma_f32_16x16x32_bf16 v[112:115], v[172:175], v[28:31], v[24:27]
	v_mfma_f32_16x16x32_bf16 v[24:27], v[160:163], v[40:43], v[84:87]
	v_mfma_f32_16x16x32_bf16 v[100:103], v[164:167], v[44:47], v[24:27]
	v_mfma_f32_16x16x32_bf16 v[24:27], v[168:171], v[40:43], v[80:83]
	v_mfma_f32_16x16x32_bf16 v[116:119], v[164:167], v[28:31], v[96:99]
	v_mfma_f32_16x16x32_bf16 v[96:99], v[172:175], v[44:47], v[24:27]
	v_mfma_f32_16x16x32_bf16 v[24:27], v[160:163], v[184:187], v[200:203]
	v_mfma_f32_16x16x32_bf16 v[84:87], v[164:167], v[188:191], v[24:27]
	v_mfma_f32_16x16x32_bf16 v[24:27], v[168:171], v[184:187], v[204:207]
	v_mfma_f32_16x16x32_bf16 v[80:83], v[172:175], v[188:191], v[24:27]
	v_mfma_f32_16x16x32_bf16 v[24:27], v[160:163], v[212:215], v[68:71]
	v_mfma_f32_16x16x32_bf16 v[68:71], v[164:167], v[236:239], v[24:27]
	v_mfma_f32_16x16x32_bf16 v[24:27], v[168:171], v[212:215], v[64:67]
	v_mfma_f32_16x16x32_bf16 v[64:67], v[172:175], v[236:239], v[24:27]
	s_barrier
	ds_read_b128 v[200:203], v226 offset:0
	ds_read_b128 v[204:207], v226 offset:0x400
	ds_read_b128 v[192:195], v226 offset:0x800
	ds_read_b128 v[196:199], v226 offset:0xc00
	ds_read_b128 v[184:187], v226 offset:0x1000
	ds_read_b128 v[188:191], v226 offset:0x1400
	ds_read_b128 v[176:179], v226 offset:0x1800
	ds_read_b128 v[180:183], v226 offset:0x1c00
	s_and_b64 vcc, exec, s[70:71]
	v_lshl_add_u64 v[212:213], s[74:75], 0, v[208:209]
	v_lshl_add_u64 v[214:215], s[72:73], 0, v[208:209]
	s_cbranch_vccz .LBB0_84
	s_mov_b32 m0, s19
	v_lshl_add_u64 v[24:25], v[212:213], 0, s[22:23]
	global_load_lds_dwordx4 v[212:213], off
	s_mov_b32 m0, s30
	s_nop 0
	global_load_lds_dwordx4 v[24:25], off
	s_mov_b32 m0, s3
	v_lshl_add_u64 v[24:25], v[214:215], 0, s[22:23]
	global_load_lds_dwordx4 v[214:215], off
	s_mov_b32 m0, s31
	s_nop 0
	global_load_lds_dwordx4 v[24:25], off
	v_lshl_add_u64 v[24:25], v[212:213], 0, s[24:25]
	s_mov_b32 m0, s50
	s_nop 0
	global_load_lds_dwordx4 v[24:25], off
	v_lshl_add_u64 v[24:25], v[212:213], 0, s[26:27]
	s_mov_b32 m0, s51
	s_nop 0
	global_load_lds_dwordx4 v[24:25], off
	v_lshl_add_u64 v[24:25], v[214:215], 0, s[24:25]
	s_mov_b32 m0, s64
	s_nop 0
	global_load_lds_dwordx4 v[24:25], off
	v_lshl_add_u64 v[24:25], v[214:215], 0, s[26:27]
	s_mov_b32 m0, s65
	s_nop 0
	global_load_lds_dwordx4 v[24:25], off

; #define SCHED() __builtin_amdgcn_sched_barrier(0)
; #define LGKM(n) asm volatile("s_waitcnt lgkmcnt(%0)" ::"n"(n) : "memory")
; #define STAGE_A(b, h, kt) STAGE_AX(Ag, b, h, kt)
; #define STAGE_B(b, h, kt) STAGE_BX(Bg, b, h, kt)
; #define LDA(b, h) do { const unsigned pa_ = lds0 + SLOTA(b, h) + wr * 8192 + laneoff; _Pragma("unroll") for (int m = 0; m < 4; ++m)   \
;       _Pragma("unroll") for (int k = 0; k < 2; ++k) DSR(At[m][k], pa_, m * 2048 + k * 1024); } while (0)
; #define LDB(dst, b, h) do { const unsigned pb_ = lds0 + SLOTB(b, h) + wc * 4096 + laneoff; _Pragma("unroll") for (int n = 0; n < 2; ++n) \
;       _Pragma("unroll") for (int k = 0; k < 2; ++k) DSR(dst[n][k], pb_, n * 2048 + k * 1024); } while (0)
; #define BAR __builtin_amdgcn_s_barrier()
; #define LGKM(n) asm volatile("s_waitcnt lgkmcnt(%0)" ::"n"(n) : "memory")
; template <int EPI, bool SWP> ...
;     ...
;     LDB(B0, 0, 0); LDA(0, 0); STAGE_A(1, 1, t + 1);
;     LGKM(8); BAR; LGKM(0); SCHED(); MMA(0, 0, B0); BAR; SCHED();
;     LDB(B1, 0, 1); STAGE_B(0, 0, t + 2);
;     BAR; LGKM(0); SCHED(); MMA(0, 1, B1); BAR; SCHED();
;     LDA(0, 1); STAGE_A(0, 0, t + 2);
;     BAR; LGKM(0); SCHED(); MMA(1, 0, B0); BAR; SCHED();
.LBB0_667:
	ds_read_b128 v[128:131], v219 offset:0
	ds_read_b128 v[132:135], v219 offset:0x400
	ds_read_b128 v[136:139], v219 offset:0x800
	ds_read_b128 v[140:143], v219 offset:0xc00
	ds_read_b128 v[144:147], v220 offset:0
	ds_read_b128 v[148:151], v220 offset:0x400
	ds_read_b128 v[152:155], v220 offset:0x800
	ds_read_b128 v[156:159], v220 offset:0xc00
	ds_read_b128 v[160:163], v220 offset:0x1000
	ds_read_b128 v[164:167], v220 offset:0x1400
	ds_read_b128 v[168:171], v220 offset:0x1800
	v_lshl_add_u64 v[192:193], s[68:69], 0, v[210:211]
	s_mov_b64 s[70:71], 0xc080080
	s_mov_b32 m0, s87
	ds_read_b128 v[172:175], v220 offset:0x1c00
	s_mov_b64 s[70:71], 0xc0c0080
	s_add_u32 s94, s68, 0xc080080
	s_addc_u32 s95, s69, 0
	global_load_lds_dwordx4 v210, s[94:95]
	s_mov_b32 m0, s88
	s_nop 0
	s_add_u32 s94, s68, 0xc0c0080
	s_addc_u32 s95, s69, 0
	global_load_lds_dwordx4 v210, s[94:95]
	s_waitcnt lgkmcnt(8)
	s_barrier
	s_waitcnt lgkmcnt(0)
	v_mfma_f32_16x16x32_bf16 v[124:127], v[128:131], v[144:147], v[124:127]
	v_mfma_f32_16x16x32_bf16 v[120:123], v[136:139], v[144:147], v[120:123]
	v_mfma_f32_16x16x32_bf16 v[116:119], v[128:131], v[152:155], v[116:119]
	v_mfma_f32_16x16x32_bf16 v[112:115], v[136:139], v[152:155], v[112:115]
	v_mfma_f32_16x16x32_bf16 v[108:111], v[128:131], v[160:163], v[108:111]
	v_mfma_f32_16x16x32_bf16 v[104:107], v[136:139], v[160:163], v[104:107]
	v_mfma_f32_16x16x32_bf16 v[100:103], v[128:131], v[168:171], v[100:103]
	v_mfma_f32_16x16x32_bf16 v[96:99], v[136:139], v[168:171], v[96:99]
	v_mfma_f32_16x16x32_bf16 v[124:127], v[132:135], v[148:151], v[124:127]
	v_mfma_f32_16x16x32_bf16 v[120:123], v[140:143], v[148:151], v[120:123]
	v_mfma_f32_16x16x32_bf16 v[116:119], v[132:135], v[156:159], v[116:119]
	v_mfma_f32_16x16x32_bf16 v[112:115], v[140:143], v[156:159], v[112:115]
	v_mfma_f32_16x16x32_bf16 v[108:111], v[132:135], v[164:167], v[108:111]
	v_mfma_f32_16x16x32_bf16 v[104:107], v[140:143], v[164:167], v[104:107]
	v_mfma_f32_16x16x32_bf16 v[100:103], v[132:135], v[172:175], v[100:103]
	v_mfma_f32_16x16x32_bf16 v[96:99], v[140:143], v[172:175], v[96:99]
	s_barrier
	ds_read_b128 v[176:179], v221 offset:0
	ds_read_b128 v[180:183], v221 offset:0x400
	ds_read_b128 v[184:187], v221 offset:0x800
	v_lshl_add_u64 v[194:195], s[66:67], 0, v[210:211]
	s_mov_b64 s[70:71], 0x2d100100
	s_mov_b32 m0, s75
	ds_read_b128 v[188:191], v221 offset:0xc00
	s_mov_b64 s[70:71], 0x2d140100
	s_add_u32 s94, s66, 0x2d100100
	s_addc_u32 s95, s67, 0
	global_load_lds_dwordx4 v210, s[94:95]
	s_mov_b32 m0, s76
	s_nop 0
	s_add_u32 s94, s66, 0x2d140100
	s_addc_u32 s95, s67, 0
	global_load_lds_dwordx4 v210, s[94:95]
	s_barrier
	s_waitcnt lgkmcnt(0)
	v_mfma_f32_16x16x32_bf16 v[92:95], v[176:179], v[144:147], v[92:95]
	v_mfma_f32_16x16x32_bf16 v[88:91], v[184:187], v[144:147], v[88:91]
	v_mfma_f32_16x16x32_bf16 v[84:87], v[176:179], v[152:155], v[84:87]
	v_mfma_f32_16x16x32_bf16 v[80:83], v[184:187], v[152:155], v[80:83]
	v_mfma_f32_16x16x32_bf16 v[76:79], v[176:179], v[160:163], v[76:79]
	v_mfma_f32_16x16x32_bf16 v[72:75], v[184:187], v[160:163], v[72:75]
	v_mfma_f32_16x16x32_bf16 v[68:71], v[176:179], v[168:171], v[68:71]
	v_mfma_f32_16x16x32_bf16 v[64:67], v[184:187], v[168:171], v[64:67]
	v_mfma_f32_16x16x32_bf16 v[92:95], v[180:183], v[148:151], v[92:95]
	v_mfma_f32_16x16x32_bf16 v[88:91], v[188:191], v[148:151], v[88:91]
	v_mfma_f32_16x16x32_bf16 v[84:87], v[180:183], v[156:159], v[84:87]
	v_mfma_f32_16x16x32_bf16 v[80:83], v[188:191], v[156:159], v[80:83]
	v_mfma_f32_16x16x32_bf16 v[76:79], v[180:183], v[164:167], v[76:79]
	v_mfma_f32_16x16x32_bf16 v[72:75], v[188:191], v[164:167], v[72:75]
	v_mfma_f32_16x16x32_bf16 v[68:71], v[180:183], v[172:175], v[68:71]
	v_mfma_f32_16x16x32_bf16 v[64:67], v[188:191], v[172:175], v[64:67]
	s_barrier
	ds_read_b128 v[144:147], v222 offset:0
	ds_read_b128 v[148:151], v222 offset:0x400
	ds_read_b128 v[152:155], v222 offset:0x800
	ds_read_b128 v[156:159], v222 offset:0xc00
	ds_read_b128 v[160:163], v222 offset:0x1000
	ds_read_b128 v[164:167], v222 offset:0x1400
	ds_read_b128 v[168:171], v222 offset:0x1800
	s_mov_b64 s[70:71], 0xc000100
	s_mov_b32 m0, s3
	ds_read_b128 v[172:175], v222 offset:0x1c00
	s_mov_b64 s[70:71], 0xc040100
	s_add_u32 s94, s68, 0xc000100
	s_addc_u32 s95, s69, 0
	global_load_lds_dwordx4 v210, s[94:95]
	s_mov_b32 m0, s77
	s_nop 0
	s_add_u32 s94, s68, 0xc040100
	s_addc_u32 s95, s69, 0
	global_load_lds_dwordx4 v210, s[94:95]
	s_barrier
	s_waitcnt lgkmcnt(0)
	v_mfma_f32_16x16x32_bf16 v[60:63], v[128:131], v[144:147], v[60:63]
	v_mfma_f32_16x16x32_bf16 v[56:59], v[136:139], v[144:147], v[56:59]
	v_mfma_f32_16x16x32_bf16 v[52:55], v[128:131], v[152:155], v[52:55]
	v_mfma_f32_16x16x32_bf16 v[48:51], v[136:139], v[152:155], v[48:51]
	v_mfma_f32_16x16x32_bf16 v[44:47], v[128:131], v[160:163], v[44:47]
	v_mfma_f32_16x16x32_bf16 v[40:43], v[136:139], v[160:163], v[40:43]
	v_mfma_f32_16x16x32_bf16 v[36:39], v[128:131], v[168:171], v[36:39]
	v_mfma_f32_16x16x32_bf16 v[32:35], v[136:139], v[168:171], v[32:35]
	v_mfma_f32_16x16x32_bf16 v[60:63], v[132:135], v[148:151], v[60:63]
	v_mfma_f32_16x16x32_bf16 v[56:59], v[140:143], v[148:151], v[56:59]
	v_mfma_f32_16x16x32_bf16 v[52:55], v[132:135], v[156:159], v[52:55]
	v_mfma_f32_16x16x32_bf16 v[48:51], v[140:143], v[156:159], v[48:51]
	v_mfma_f32_16x16x32_bf16 v[44:47], v[132:135], v[164:167], v[44:47]
	v_mfma_f32_16x16x32_bf16 v[40:43], v[140:143], v[164:167], v[40:43]
	v_mfma_f32_16x16x32_bf16 v[36:39], v[132:135], v[172:175], v[36:39]
	v_mfma_f32_16x16x32_bf16 v[32:35], v[140:143], v[172:175], v[32:35]
	s_barrier
; #define WAIT_V(n) asm volatile("s_waitcnt vmcnt(%0)" ::"n"(n) : "memory")
; #define SCHED() __builtin_amdgcn_sched_barrier(0)
; #define LGKM(n) asm volatile("s_waitcnt lgkmcnt(%0)" ::"n"(n) : "memory")
; #define STAGE_A(b, h, kt) STAGE_AX(Ag, b, h, kt)
; #define STAGE_B(b, h, kt) STAGE_BX(Bg, b, h, kt)
; #define LDA(b, h) do { const unsigned pa_ = lds0 + SLOTA(b, h) + wr * 8192 + laneoff; _Pragma("unroll") for (int m = 0; m < 4; ++m)   \
;       _Pragma("unroll") for (int k = 0; k < 2; ++k) DSR(At[m][k], pa_, m * 2048 + k * 1024); } while (0)
; #define LDB(dst, b, h) do { const unsigned pb_ = lds0 + SLOTB(b, h) + wc * 4096 + laneoff; _Pragma("unroll") for (int n = 0; n < 2; ++n) \
;       _Pragma("unroll") for (int k = 0; k < 2; ++k) DSR(dst[n][k], pb_, n * 2048 + k * 1024); } while (0)
; #define BAR __builtin_amdgcn_s_barrier()
; #define LGKM(n) asm volatile("s_waitcnt lgkmcnt(%0)" ::"n"(n) : "memory")
; template <int EPI, bool SWP> ...
;     ...
;     STAGE_B(0, 1, t + 2);
;     WAIT_V(6); BAR; SCHED(); MMA(1, 1, B1); BAR; SCHED();
;     LDB(B0, 1, 0); LDA(1, 0); STAGE_A(0, 1, t + 2);
;     LGKM(8); BAR; LGKM(0); SCHED(); MMA(0, 0, B0); BAR; SCHED();
;     LDB(B1, 1, 1); STAGE_B(1, 0, t + 3);
;     BAR; LGKM(0); SCHED(); MMA(0, 1, B1); BAR; SCHED();
;     LDA(1, 1); STAGE_A(1, 0, t + 3);
	s_mov_b64 s[70:71], 0x2d180100
	s_mov_b32 m0, s78
	s_mov_b64 s[70:71], 0x2d1c0100
	s_add_u32 s94, s66, 0x2d180100
	s_addc_u32 s95, s67, 0
	global_load_lds_dwordx4 v210, s[94:95]
	s_mov_b32 m0, s79
	s_nop 0
	s_add_u32 s94, s66, 0x2d1c0100
	s_addc_u32 s95, s67, 0
	global_load_lds_dwordx4 v210, s[94:95]
	s_waitcnt vmcnt(6)
	s_barrier
	v_mfma_f32_16x16x32_bf16 v[28:31], v[176:179], v[144:147], v[28:31]
	v_mfma_f32_16x16x32_bf16 v[24:27], v[184:187], v[144:147], v[24:27]
	v_mfma_f32_16x16x32_bf16 v[20:23], v[176:179], v[152:155], v[20:23]
	v_mfma_f32_16x16x32_bf16 v[16:19], v[184:187], v[152:155], v[16:19]
	v_mfma_f32_16x16x32_bf16 v[12:15], v[176:179], v[160:163], v[12:15]
	v_mfma_f32_16x16x32_bf16 v[8:11], v[184:187], v[160:163], v[8:11]
	v_mfma_f32_16x16x32_bf16 v[4:7], v[176:179], v[168:171], v[4:7]
	v_mfma_f32_16x16x32_bf16 v[0:3], v[184:187], v[168:171], v[0:3]
	v_mfma_f32_16x16x32_bf16 v[28:31], v[180:183], v[148:151], v[28:31]
	v_mfma_f32_16x16x32_bf16 v[24:27], v[188:191], v[148:151], v[24:27]
	v_mfma_f32_16x16x32_bf16 v[20:23], v[180:183], v[156:159], v[20:23]
	v_mfma_f32_16x16x32_bf16 v[16:19], v[188:191], v[156:159], v[16:19]
	v_mfma_f32_16x16x32_bf16 v[12:15], v[180:183], v[164:167], v[12:15]
	v_mfma_f32_16x16x32_bf16 v[8:11], v[188:191], v[164:167], v[8:11]
	v_mfma_f32_16x16x32_bf16 v[4:7], v[180:183], v[172:175], v[4:7]
	v_mfma_f32_16x16x32_bf16 v[0:3], v[188:191], v[172:175], v[0:3]
	s_barrier
	ds_read_b128 v[128:131], v223 offset:0
	ds_read_b128 v[132:135], v223 offset:0x400
	ds_read_b128 v[136:139], v223 offset:0x800
	ds_read_b128 v[140:143], v223 offset:0xc00
	ds_read_b128 v[144:147], v224 offset:0
	ds_read_b128 v[148:151], v224 offset:0x400
	ds_read_b128 v[152:155], v224 offset:0x800
	ds_read_b128 v[156:159], v224 offset:0xc00
	ds_read_b128 v[160:163], v224 offset:0x1000
	ds_read_b128 v[164:167], v224 offset:0x1400
	ds_read_b128 v[168:171], v224 offset:0x1800
	s_mov_b64 s[70:71], 0xc080100
	s_mov_b32 m0, s80
	ds_read_b128 v[172:175], v224 offset:0x1c00
	s_mov_b64 s[70:71], 0xc0c0100
	s_add_u32 s94, s68, 0xc080100
	s_addc_u32 s95, s69, 0
	global_load_lds_dwordx4 v210, s[94:95]
	s_mov_b32 m0, s81
	s_nop 0
	s_add_u32 s94, s68, 0xc0c0100
	s_addc_u32 s95, s69, 0
	global_load_lds_dwordx4 v210, s[94:95]
	s_waitcnt lgkmcnt(8)
	s_barrier
	s_waitcnt lgkmcnt(0)
	v_mfma_f32_16x16x32_bf16 v[124:127], v[128:131], v[144:147], v[124:127]
	v_mfma_f32_16x16x32_bf16 v[120:123], v[136:139], v[144:147], v[120:123]
	v_mfma_f32_16x16x32_bf16 v[116:119], v[128:131], v[152:155], v[116:119]
	v_mfma_f32_16x16x32_bf16 v[112:115], v[136:139], v[152:155], v[112:115]
	v_mfma_f32_16x16x32_bf16 v[108:111], v[128:131], v[160:163], v[108:111]
	v_mfma_f32_16x16x32_bf16 v[104:107], v[136:139], v[160:163], v[104:107]
	v_mfma_f32_16x16x32_bf16 v[100:103], v[128:131], v[168:171], v[100:103]
	v_mfma_f32_16x16x32_bf16 v[96:99], v[136:139], v[168:171], v[96:99]
	v_mfma_f32_16x16x32_bf16 v[124:127], v[132:135], v[148:151], v[124:127]
	v_mfma_f32_16x16x32_bf16 v[120:123], v[140:143], v[148:151], v[120:123]
	v_mfma_f32_16x16x32_bf16 v[116:119], v[132:135], v[156:159], v[116:119]
	v_mfma_f32_16x16x32_bf16 v[112:115], v[140:143], v[156:159], v[112:115]
	v_mfma_f32_16x16x32_bf16 v[108:111], v[132:135], v[164:167], v[108:111]
	v_mfma_f32_16x16x32_bf16 v[104:107], v[140:143], v[164:167], v[104:107]
	v_mfma_f32_16x16x32_bf16 v[100:103], v[132:135], v[172:175], v[100:103]
	v_mfma_f32_16x16x32_bf16 v[96:99], v[140:143], v[172:175], v[96:99]
	s_barrier
	ds_read_b128 v[176:179], v225 offset:0
	ds_read_b128 v[180:183], v225 offset:0x400
	ds_read_b128 v[184:187], v225 offset:0x800
	s_mov_b64 s[70:71], 0x2d100180
	s_mov_b32 m0, s82
	ds_read_b128 v[188:191], v225 offset:0xc00
	s_mov_b64 s[70:71], 0x2d140180
	s_add_u32 s94, s66, 0x2d100180
	s_addc_u32 s95, s67, 0
	global_load_lds_dwordx4 v210, s[94:95]
	s_mov_b32 m0, s83
	s_nop 0
	s_add_u32 s94, s66, 0x2d140180
	s_addc_u32 s95, s67, 0
	global_load_lds_dwordx4 v210, s[94:95]
	s_barrier
	s_waitcnt lgkmcnt(0)
	v_mfma_f32_16x16x32_bf16 v[92:95], v[176:179], v[144:147], v[92:95]
	v_mfma_f32_16x16x32_bf16 v[88:91], v[184:187], v[144:147], v[88:91]
	v_mfma_f32_16x16x32_bf16 v[84:87], v[176:179], v[152:155], v[84:87]
	v_mfma_f32_16x16x32_bf16 v[80:83], v[184:187], v[152:155], v[80:83]
	v_mfma_f32_16x16x32_bf16 v[76:79], v[176:179], v[160:163], v[76:79]
	v_mfma_f32_16x16x32_bf16 v[72:75], v[184:187], v[160:163], v[72:75]
	v_mfma_f32_16x16x32_bf16 v[68:71], v[176:179], v[168:171], v[68:71]
	v_mfma_f32_16x16x32_bf16 v[64:67], v[184:187], v[168:171], v[64:67]
	v_mfma_f32_16x16x32_bf16 v[92:95], v[180:183], v[148:151], v[92:95]
	v_mfma_f32_16x16x32_bf16 v[88:91], v[188:191], v[148:151], v[88:91]
	v_mfma_f32_16x16x32_bf16 v[84:87], v[180:183], v[156:159], v[84:87]
	v_mfma_f32_16x16x32_bf16 v[80:83], v[188:191], v[156:159], v[80:83]
	v_mfma_f32_16x16x32_bf16 v[76:79], v[180:183], v[164:167], v[76:79]
	v_mfma_f32_16x16x32_bf16 v[72:75], v[188:191], v[164:167], v[72:75]
	v_mfma_f32_16x16x32_bf16 v[68:71], v[180:183], v[172:175], v[68:71]
	v_mfma_f32_16x16x32_bf16 v[64:67], v[188:191], v[172:175], v[64:67]
	s_barrier
	ds_read_b128 v[144:147], v226 offset:0
	ds_read_b128 v[148:151], v226 offset:0x400
	ds_read_b128 v[152:155], v226 offset:0x800
	ds_read_b128 v[156:159], v226 offset:0xc00
	ds_read_b128 v[160:163], v226 offset:0x1000
	ds_read_b128 v[164:167], v226 offset:0x1400
	ds_read_b128 v[168:171], v226 offset:0x1800
	s_mov_b32 m0, s84
	ds_read_b128 v[172:175], v226 offset:0x1c00
	s_add_u32 s94, s68, s36
	s_addc_u32 s95, s69, s37
	global_load_lds_dwordx4 v210, s[94:95]
	v_lshl_add_u64 v[192:193], v[192:193], 0, s[38:39]
	s_mov_b32 m0, s85
	s_nop 0
	s_add_u32 s94, s68, s38
	s_addc_u32 s95, s69, s39
	global_load_lds_dwordx4 v210, s[94:95]
	s_barrier
; #define WAIT_V(n) asm volatile("s_waitcnt vmcnt(%0)" ::"n"(n) : "memory")
; #define SCHED() __builtin_amdgcn_sched_barrier(0)
; #define LGKM(n) asm volatile("s_waitcnt lgkmcnt(%0)" ::"n"(n) : "memory")
; #define STAGE_A(b, h, kt) STAGE_AX(Ag, b, h, kt)
; #define STAGE_B(b, h, kt) STAGE_BX(Bg, b, h, kt)
; #define LDA(b, h) do { const unsigned pa_ = lds0 + SLOTA(b, h) + wr * 8192 + laneoff; _Pragma("unroll") for (int m = 0; m < 4; ++m)   \
;       _Pragma("unroll") for (int k = 0; k < 2; ++k) DSR(At[m][k], pa_, m * 2048 + k * 1024); } while (0)
; #define LDB(dst, b, h) do { const unsigned pb_ = lds0 + SLOTB(b, h) + wc * 4096 + laneoff; _Pragma("unroll") for (int n = 0; n < 2; ++n) \
;       _Pragma("unroll") for (int k = 0; k < 2; ++k) DSR(dst[n][k], pb_, n * 2048 + k * 1024); } while (0)
; #define BAR __builtin_amdgcn_s_barrier()
; #define LGKM(n) asm volatile("s_waitcnt lgkmcnt(%0)" ::"n"(n) : "memory")
; template <int EPI, bool SWP> ...
;     ...
;     BAR; LGKM(0); SCHED(); MMA(1, 0, B0); BAR; SCHED();
;     STAGE_B(1, 1, t + 3);
;     WAIT_V(6); BAR; SCHED(); MMA(1, 1, B1); BAR; SCHED();
;   }
;   { LDB(B0, 0, 0); LDA(0, 0); STAGE_A(1, 1, nt - 1);
;     BAR; LGKM(0); SCHED(); MMA(0, 0, B0); BAR; SCHED();
;     LDB(B1, 0, 1); BAR; LGKM(0); SCHED(); MMA(0, 1, B1); BAR; SCHED();
	s_waitcnt lgkmcnt(0)
	v_mfma_f32_16x16x32_bf16 v[60:63], v[128:131], v[144:147], v[60:63]
	v_mfma_f32_16x16x32_bf16 v[56:59], v[136:139], v[144:147], v[56:59]
	v_mfma_f32_16x16x32_bf16 v[52:55], v[128:131], v[152:155], v[52:55]
	v_mfma_f32_16x16x32_bf16 v[48:51], v[136:139], v[152:155], v[48:51]
	v_mfma_f32_16x16x32_bf16 v[44:47], v[128:131], v[160:163], v[44:47]
	v_mfma_f32_16x16x32_bf16 v[40:43], v[136:139], v[160:163], v[40:43]
	v_mfma_f32_16x16x32_bf16 v[36:39], v[128:131], v[168:171], v[36:39]
	v_mfma_f32_16x16x32_bf16 v[32:35], v[136:139], v[168:171], v[32:35]
	v_mfma_f32_16x16x32_bf16 v[60:63], v[132:135], v[148:151], v[60:63]
	v_mfma_f32_16x16x32_bf16 v[56:59], v[140:143], v[148:151], v[56:59]
	v_mfma_f32_16x16x32_bf16 v[52:55], v[132:135], v[156:159], v[52:55]
	v_mfma_f32_16x16x32_bf16 v[48:51], v[140:143], v[156:159], v[48:51]
	v_mfma_f32_16x16x32_bf16 v[44:47], v[132:135], v[164:167], v[44:47]
	v_mfma_f32_16x16x32_bf16 v[40:43], v[140:143], v[164:167], v[40:43]
	v_mfma_f32_16x16x32_bf16 v[36:39], v[132:135], v[172:175], v[36:39]
	v_mfma_f32_16x16x32_bf16 v[32:35], v[140:143], v[172:175], v[32:35]
	s_barrier
	s_add_i32 s70, s3, 0x1c000
	s_mov_b32 m0, s70
	s_nop 0
	s_add_u32 s94, s66, s40
	s_addc_u32 s95, s67, s41
	global_load_lds_dwordx4 v210, s[94:95]
	s_mov_b32 m0, s86
	s_nop 0
	s_add_u32 s94, s66, s42
	s_addc_u32 s95, s67, s43
	global_load_lds_dwordx4 v210, s[94:95]
	s_waitcnt vmcnt(6)
	s_barrier
	v_mfma_f32_16x16x32_bf16 v[28:31], v[176:179], v[144:147], v[28:31]
	v_mfma_f32_16x16x32_bf16 v[24:27], v[184:187], v[144:147], v[24:27]
	v_mfma_f32_16x16x32_bf16 v[20:23], v[176:179], v[152:155], v[20:23]
	v_mfma_f32_16x16x32_bf16 v[16:19], v[184:187], v[152:155], v[16:19]
	v_mfma_f32_16x16x32_bf16 v[12:15], v[176:179], v[160:163], v[12:15]
	v_mfma_f32_16x16x32_bf16 v[8:11], v[184:187], v[160:163], v[8:11]
	v_mfma_f32_16x16x32_bf16 v[4:7], v[176:179], v[168:171], v[4:7]
	v_mfma_f32_16x16x32_bf16 v[0:3], v[184:187], v[168:171], v[0:3]
	v_mfma_f32_16x16x32_bf16 v[28:31], v[180:183], v[148:151], v[28:31]
	v_mfma_f32_16x16x32_bf16 v[24:27], v[188:191], v[148:151], v[24:27]
	v_mfma_f32_16x16x32_bf16 v[20:23], v[180:183], v[156:159], v[20:23]
	v_mfma_f32_16x16x32_bf16 v[16:19], v[188:191], v[156:159], v[16:19]
	v_mfma_f32_16x16x32_bf16 v[12:15], v[180:183], v[164:167], v[12:15]
	v_mfma_f32_16x16x32_bf16 v[8:11], v[188:191], v[164:167], v[8:11]
	v_mfma_f32_16x16x32_bf16 v[4:7], v[180:183], v[172:175], v[4:7]
	v_mfma_f32_16x16x32_bf16 v[0:3], v[188:191], v[172:175], v[0:3]
	s_add_i32 s1, s1, 2
	s_add_u32 s66, s66, 0x100
	s_addc_u32 s67, s67, 0
	s_add_u32 s68, s68, 0x100
	s_addc_u32 s69, s69, 0
	s_cmp_gt_u32 s1, 27
	s_barrier
	s_cbranch_scc0 .LBB0_667
	ds_read_b128 v[136:139], v219 offset:0
	ds_read_b128 v[140:143], v219 offset:0x400
	ds_read_b128 v[144:147], v219 offset:0x800
	ds_read_b128 v[148:151], v219 offset:0xc00
	ds_read_b128 v[128:131], v220 offset:0
	ds_read_b128 v[132:135], v220 offset:0x400
	ds_read_b128 v[152:155], v220 offset:0x800
	ds_read_b128 v[156:159], v220 offset:0xc00
	ds_read_b128 v[160:163], v220 offset:0x1000
	ds_read_b128 v[164:167], v220 offset:0x1400
	v_lshl_add_u64 v[176:177], s[64:65], 0, v[208:209]
	ds_read_b128 v[168:171], v220 offset:0x1800
	s_mov_b32 m0, s87
	ds_read_b128 v[172:175], v220 offset:0x1c00
	v_lshl_add_u64 v[178:179], v[176:177], 0, s[44:45]
	global_load_lds_dwordx4 v[178:179], off
	v_lshl_add_u64 v[176:177], v[176:177], 0, s[46:47]
	s_mov_b32 m0, s88
	s_ashr_i32 s1, s0, 31
	global_load_lds_dwordx4 v[176:177], off
	s_lshl_b64 s[64:65], s[0:1], 20
	s_add_u32 s64, s24, s64
	s_addc_u32 s65, s25, s65
	s_ashr_i32 s51, s50, 31
	s_barrier
	s_waitcnt lgkmcnt(0)
	s_lshl_b64 s[66:67], s[50:51], 20
	s_add_u32 s66, s30, s66
	s_addc_u32 s67, s31, s67
	v_mfma_f32_16x16x32_bf16 v[124:127], v[136:139], v[128:131], v[124:127]
	v_mfma_f32_16x16x32_bf16 v[120:123], v[144:147], v[128:131], v[120:123]
	v_mfma_f32_16x16x32_bf16 v[116:119], v[136:139], v[152:155], v[116:119]
	v_mfma_f32_16x16x32_bf16 v[112:115], v[144:147], v[152:155], v[112:115]
	v_mfma_f32_16x16x32_bf16 v[108:111], v[136:139], v[160:163], v[108:111]
	v_mfma_f32_16x16x32_bf16 v[104:107], v[144:147], v[160:163], v[104:107]
	v_mfma_f32_16x16x32_bf16 v[100:103], v[136:139], v[168:171], v[100:103]
	v_mfma_f32_16x16x32_bf16 v[96:99], v[144:147], v[168:171], v[96:99]
	v_mfma_f32_16x16x32_bf16 v[124:127], v[140:143], v[132:135], v[124:127]
	v_mfma_f32_16x16x32_bf16 v[120:123], v[148:151], v[132:135], v[120:123]
	v_mfma_f32_16x16x32_bf16 v[116:119], v[140:143], v[156:159], v[116:119]
	v_mfma_f32_16x16x32_bf16 v[112:115], v[148:151], v[156:159], v[112:115]
	v_mfma_f32_16x16x32_bf16 v[176:179], v[140:143], v[164:167], v[108:111]
	v_mfma_f32_16x16x32_bf16 v[180:183], v[148:151], v[164:167], v[104:107]
	v_mfma_f32_16x16x32_bf16 v[100:103], v[140:143], v[172:175], v[100:103]
	v_mfma_f32_16x16x32_bf16 v[96:99], v[148:151], v[172:175], v[96:99]
	s_barrier
	ds_read_b128 v[104:107], v221 offset:0
	ds_read_b128 v[108:111], v221 offset:0x400
	ds_read_b128 v[184:187], v221 offset:0x800
	ds_read_b128 v[188:191], v221 offset:0xc00
	s_barrier
; #define WAIT_V(n) asm volatile("s_waitcnt vmcnt(%0)" ::"n"(n) : "memory")
; #define SCHED() __builtin_amdgcn_sched_barrier(0)
; #define LGKM(n) asm volatile("s_waitcnt lgkmcnt(%0)" ::"n"(n) : "memory")
; #define LDA(b, h) do { const unsigned pa_ = lds0 + SLOTA(b, h) + wr * 8192 + laneoff; _Pragma("unroll") for (int m = 0; m < 4; ++m)   \
;       _Pragma("unroll") for (int k = 0; k < 2; ++k) DSR(At[m][k], pa_, m * 2048 + k * 1024); } while (0)
; #define LDB(dst, b, h) do { const unsigned pb_ = lds0 + SLOTB(b, h) + wc * 4096 + laneoff; _Pragma("unroll") for (int n = 0; n < 2; ++n) \
;       _Pragma("unroll") for (int k = 0; k < 2; ++k) DSR(dst[n][k], pb_, n * 2048 + k * 1024); } while (0)
; #define BAR __builtin_amdgcn_s_barrier()
; #define LGKM(n) asm volatile("s_waitcnt lgkmcnt(%0)" ::"n"(n) : "memory")
; template <int EPI, bool SWP> ...
;     ...
;     LDB(B1, 0, 1); BAR; LGKM(0); SCHED(); MMA(0, 1, B1); BAR; SCHED();
;     LDA(0, 1); WAIT_V(4); BAR; LGKM(0); SCHED(); MMA(1, 0, B0); MMA(1, 1, B1); BAR; SCHED(); }
;   { LDB(B0, 1, 0); LDA(1, 0); WAIT_V(2); BAR; LGKM(0); SCHED(); MMA(0, 0, B0); BAR; SCHED();
	s_waitcnt lgkmcnt(0)
	v_mfma_f32_16x16x32_bf16 v[92:95], v[104:107], v[128:131], v[92:95]
	v_mfma_f32_16x16x32_bf16 v[88:91], v[184:187], v[128:131], v[88:91]
	v_mfma_f32_16x16x32_bf16 v[84:87], v[104:107], v[152:155], v[84:87]
	v_mfma_f32_16x16x32_bf16 v[80:83], v[184:187], v[152:155], v[80:83]
	v_mfma_f32_16x16x32_bf16 v[76:79], v[104:107], v[160:163], v[76:79]
	v_mfma_f32_16x16x32_bf16 v[72:75], v[184:187], v[160:163], v[72:75]
	v_mfma_f32_16x16x32_bf16 v[68:71], v[104:107], v[168:171], v[68:71]
	v_mfma_f32_16x16x32_bf16 v[64:67], v[184:187], v[168:171], v[64:67]
	v_mfma_f32_16x16x32_bf16 v[192:195], v[108:111], v[132:135], v[92:95]
	v_mfma_f32_16x16x32_bf16 v[196:199], v[188:191], v[132:135], v[88:91]
	v_mfma_f32_16x16x32_bf16 v[84:87], v[108:111], v[156:159], v[84:87]
	v_mfma_f32_16x16x32_bf16 v[80:83], v[188:191], v[156:159], v[80:83]
	v_mfma_f32_16x16x32_bf16 v[200:203], v[108:111], v[164:167], v[76:79]
	v_mfma_f32_16x16x32_bf16 v[204:207], v[188:191], v[164:167], v[72:75]
	v_mfma_f32_16x16x32_bf16 v[68:71], v[108:111], v[172:175], v[68:71]
	v_mfma_f32_16x16x32_bf16 v[64:67], v[188:191], v[172:175], v[64:67]
	s_barrier
	ds_read_b128 v[72:75], v222 offset:0
	ds_read_b128 v[76:79], v222 offset:0x400
	ds_read_b128 v[88:91], v222 offset:0x800
	ds_read_b128 v[92:95], v222 offset:0xc00
	ds_read_b128 v[152:155], v222 offset:0x1000
	ds_read_b128 v[156:159], v222 offset:0x1400
	ds_read_b128 v[160:163], v222 offset:0x1800
	ds_read_b128 v[164:167], v222 offset:0x1c00
	s_waitcnt vmcnt(4)
	s_barrier
	s_waitcnt lgkmcnt(0)
	v_mfma_f32_16x16x32_bf16 v[60:63], v[136:139], v[72:75], v[60:63]
	v_mfma_f32_16x16x32_bf16 v[56:59], v[144:147], v[72:75], v[56:59]
	v_mfma_f32_16x16x32_bf16 v[52:55], v[136:139], v[88:91], v[52:55]
	v_mfma_f32_16x16x32_bf16 v[48:51], v[144:147], v[88:91], v[48:51]
	v_mfma_f32_16x16x32_bf16 v[44:47], v[136:139], v[152:155], v[44:47]
	v_mfma_f32_16x16x32_bf16 v[40:43], v[144:147], v[152:155], v[40:43]
	v_mfma_f32_16x16x32_bf16 v[36:39], v[136:139], v[160:163], v[36:39]
	v_mfma_f32_16x16x32_bf16 v[32:35], v[144:147], v[160:163], v[32:35]
	v_mfma_f32_16x16x32_bf16 v[60:63], v[140:143], v[76:79], v[60:63]
	v_mfma_f32_16x16x32_bf16 v[56:59], v[148:151], v[76:79], v[56:59]
	v_mfma_f32_16x16x32_bf16 v[52:55], v[140:143], v[92:95], v[52:55]
	v_mfma_f32_16x16x32_bf16 v[48:51], v[148:151], v[92:95], v[48:51]
	v_mfma_f32_16x16x32_bf16 v[128:131], v[140:143], v[156:159], v[44:47]
	v_mfma_f32_16x16x32_bf16 v[132:135], v[148:151], v[156:159], v[40:43]
	v_mfma_f32_16x16x32_bf16 v[36:39], v[140:143], v[164:167], v[36:39]
	v_mfma_f32_16x16x32_bf16 v[32:35], v[148:151], v[164:167], v[32:35]
	v_mfma_f32_16x16x32_bf16 v[28:31], v[104:107], v[72:75], v[28:31]
	v_mfma_f32_16x16x32_bf16 v[24:27], v[184:187], v[72:75], v[24:27]
	v_mfma_f32_16x16x32_bf16 v[20:23], v[104:107], v[88:91], v[20:23]
	v_mfma_f32_16x16x32_bf16 v[16:19], v[184:187], v[88:91], v[16:19]
	v_mfma_f32_16x16x32_bf16 v[12:15], v[104:107], v[152:155], v[12:15]
	v_mfma_f32_16x16x32_bf16 v[8:11], v[184:187], v[152:155], v[8:11]
	v_mfma_f32_16x16x32_bf16 v[4:7], v[104:107], v[160:163], v[4:7]
	v_mfma_f32_16x16x32_bf16 v[0:3], v[184:187], v[160:163], v[0:3]
	v_mfma_f32_16x16x32_bf16 v[136:139], v[108:111], v[76:79], v[28:31]
	v_mfma_f32_16x16x32_bf16 v[140:143], v[188:191], v[76:79], v[24:27]
	v_mfma_f32_16x16x32_bf16 v[20:23], v[108:111], v[92:95], v[20:23]
	v_mfma_f32_16x16x32_bf16 v[16:19], v[188:191], v[92:95], v[16:19]
	v_mfma_f32_16x16x32_bf16 v[144:147], v[108:111], v[156:159], v[12:15]
	v_mfma_f32_16x16x32_bf16 v[148:151], v[188:191], v[156:159], v[8:11]
	v_mfma_f32_16x16x32_bf16 v[4:7], v[108:111], v[164:167], v[4:7]
	v_mfma_f32_16x16x32_bf16 v[0:3], v[188:191], v[164:167], v[0:3]
	s_barrier
	ds_read_b128 v[8:11], v223 offset:0
	ds_read_b128 v[12:15], v223 offset:0x400
	ds_read_b128 v[152:155], v223 offset:0x800
	ds_read_b128 v[156:159], v223 offset:0xc00
	ds_read_b128 v[24:27], v224 offset:0
	ds_read_b128 v[28:31], v224 offset:0x400
	ds_read_b128 v[40:43], v224 offset:0x800
	ds_read_b128 v[44:47], v224 offset:0xc00
	ds_read_b128 v[184:187], v224 offset:0x1000
	ds_read_b128 v[188:191], v224 offset:0x1400
	ds_read_b128 v[212:215], v224 offset:0x1800
	ds_read_b128 v[236:239], v224 offset:0x1c00
	s_waitcnt vmcnt(2)
	s_barrier
; #define WAIT_V(n) asm volatile("s_waitcnt vmcnt(%0)" ::"n"(n) : "memory")
; #define SCHED() __builtin_amdgcn_sched_barrier(0)
; #define LGKM(n) asm volatile("s_waitcnt lgkmcnt(%0)" ::"n"(n) : "memory")
; #define STAGE_AX(AG, b, h, kt) do { _Pragma("unroll") for (int i = 0; i < 2; ++i)                                    \
;       __builtin_amdgcn_global_load_lds((const unsigned*)(((AG) + ((size_t)(kt) * (BK * 2) + (size_t)((h) * 2 + i) * 128 * lda)) + aoff), \
;                                        (unsigned*)(shm + SLOTA(b, h) + wid * 1024 + i * 8192), 16, 0, 0); } while (0)
; #define STAGE_BX(BG, b, h, kt) do { _Pragma("unroll") for (int i = 0; i < 2; ++i)                                    \
;       __builtin_amdgcn_global_load_lds((const unsigned*)(((BG) + ((size_t)(kt) * (BK * 2) + (size_t)((h) * 2 + i) * 128 * K)) + boff),   \
;                                        (unsigned*)(shm + SLOTB(b, h) + wid * 1024 + i * 8192), 16, 0, 0); } while (0)
; #define LDA(b, h) do { const unsigned pa_ = lds0 + SLOTA(b, h) + wr * 8192 + laneoff; _Pragma("unroll") for (int m = 0; m < 4; ++m)   \
;       _Pragma("unroll") for (int k = 0; k < 2; ++k) DSR(At[m][k], pa_, m * 2048 + k * 1024); } while (0)
; #define LDB(dst, b, h) do { const unsigned pb_ = lds0 + SLOTB(b, h) + wc * 4096 + laneoff; _Pragma("unroll") for (int n = 0; n < 2; ++n) \
;       _Pragma("unroll") for (int k = 0; k < 2; ++k) DSR(dst[n][k], pb_, n * 2048 + k * 1024); } while (0)
; #define BAR __builtin_amdgcn_s_barrier()
; #define LGKM(n) asm volatile("s_waitcnt lgkmcnt(%0)" ::"n"(n) : "memory")
; template <int EPI, bool SWP> ...
;     ...
;   { LDB(B0, 1, 0); LDA(1, 0); WAIT_V(2); BAR; LGKM(0); SCHED(); MMA(0, 0, B0); BAR; SCHED();
;     LDB(B1, 1, 1); WAIT_V(0); BAR; LGKM(0); SCHED(); MMA(0, 1, B1); BAR; SCHED();
;     LDA(1, 1);
;     if (has_next) { STAGE_BX(Bg_n, 0, 0, 0); STAGE_AX(Ag_n, 0, 0, 0); STAGE_BX(Bg_n, 0, 1, 0); STAGE_AX(Ag_n, 0, 1, 0); }
	s_waitcnt lgkmcnt(0)
	v_mfma_f32_16x16x32_bf16 v[72:75], v[8:11], v[24:27], v[124:127]
	v_mfma_f32_16x16x32_bf16 v[124:127], v[12:15], v[28:31], v[72:75]
	v_mfma_f32_16x16x32_bf16 v[72:75], v[152:155], v[24:27], v[120:123]
	v_mfma_f32_16x16x32_bf16 v[120:123], v[156:159], v[28:31], v[72:75]
	v_mfma_f32_16x16x32_bf16 v[72:75], v[8:11], v[40:43], v[116:119]
	v_mfma_f32_16x16x32_bf16 v[108:111], v[12:15], v[44:47], v[72:75]
	v_mfma_f32_16x16x32_bf16 v[72:75], v[152:155], v[40:43], v[112:115]
	v_mfma_f32_16x16x32_bf16 v[104:107], v[156:159], v[44:47], v[72:75]
	v_mfma_f32_16x16x32_bf16 v[72:75], v[8:11], v[184:187], v[176:179]
	v_mfma_f32_16x16x32_bf16 v[92:95], v[12:15], v[188:191], v[72:75]
	v_mfma_f32_16x16x32_bf16 v[72:75], v[152:155], v[184:187], v[180:183]
	v_mfma_f32_16x16x32_bf16 v[88:91], v[156:159], v[188:191], v[72:75]
	v_mfma_f32_16x16x32_bf16 v[72:75], v[8:11], v[212:215], v[100:103]
	v_mfma_f32_16x16x32_bf16 v[76:79], v[12:15], v[236:239], v[72:75]
	v_mfma_f32_16x16x32_bf16 v[72:75], v[152:155], v[212:215], v[96:99]
	v_mfma_f32_16x16x32_bf16 v[72:75], v[156:159], v[236:239], v[72:75]
	s_barrier
	ds_read_b128 v[160:163], v225 offset:0
	ds_read_b128 v[164:167], v225 offset:0x400
	ds_read_b128 v[168:171], v225 offset:0x800
	ds_read_b128 v[172:175], v225 offset:0xc00
	s_waitcnt vmcnt(0)
	s_barrier
	s_waitcnt lgkmcnt(0)
	v_mfma_f32_16x16x32_bf16 v[96:99], v[160:163], v[24:27], v[192:195]
	v_mfma_f32_16x16x32_bf16 v[24:27], v[168:171], v[24:27], v[196:199]
	v_mfma_f32_16x16x32_bf16 v[112:115], v[172:175], v[28:31], v[24:27]
	v_mfma_f32_16x16x32_bf16 v[24:27], v[160:163], v[40:43], v[84:87]
	v_mfma_f32_16x16x32_bf16 v[100:103], v[164:167], v[44:47], v[24:27]
	v_mfma_f32_16x16x32_bf16 v[24:27], v[168:171], v[40:43], v[80:83]
	v_mfma_f32_16x16x32_bf16 v[116:119], v[164:167], v[28:31], v[96:99]
	v_mfma_f32_16x16x32_bf16 v[96:99], v[172:175], v[44:47], v[24:27]
	v_mfma_f32_16x16x32_bf16 v[24:27], v[160:163], v[184:187], v[200:203]
	v_mfma_f32_16x16x32_bf16 v[84:87], v[164:167], v[188:191], v[24:27]
	v_mfma_f32_16x16x32_bf16 v[24:27], v[168:171], v[184:187], v[204:207]
	v_mfma_f32_16x16x32_bf16 v[80:83], v[172:175], v[188:191], v[24:27]
	v_mfma_f32_16x16x32_bf16 v[24:27], v[160:163], v[212:215], v[68:71]
	v_mfma_f32_16x16x32_bf16 v[68:71], v[164:167], v[236:239], v[24:27]
	v_mfma_f32_16x16x32_bf16 v[24:27], v[168:171], v[212:215], v[64:67]
	v_mfma_f32_16x16x32_bf16 v[64:67], v[172:175], v[236:239], v[24:27]
	s_barrier
	ds_read_b128 v[200:203], v226 offset:0
	ds_read_b128 v[204:207], v226 offset:0x400
	ds_read_b128 v[192:195], v226 offset:0x800
	ds_read_b128 v[196:199], v226 offset:0xc00
	ds_read_b128 v[184:187], v226 offset:0x1000
	ds_read_b128 v[188:191], v226 offset:0x1400
	ds_read_b128 v[176:179], v226 offset:0x1800
	ds_read_b128 v[180:183], v226 offset:0x1c00
	s_and_b64 vcc, exec, s[62:63]
	v_lshl_add_u64 v[212:213], s[66:67], 0, v[208:209]
	v_lshl_add_u64 v[214:215], s[64:65], 0, v[208:209]
	s_cbranch_vccz .LBB0_670
	s_mov_b32 m0, s75
	v_lshl_add_u64 v[24:25], v[212:213], 0, s[12:13]
	global_load_lds_dwordx4 v[212:213], off
	s_mov_b32 m0, s76
	s_nop 0
	global_load_lds_dwordx4 v[24:25], off
	s_mov_b32 m0, s3
	v_lshl_add_u64 v[24:25], v[214:215], 0, s[12:13]
	global_load_lds_dwordx4 v[214:215], off
	s_mov_b32 m0, s77
	s_nop 0
	global_load_lds_dwordx4 v[24:25], off
	v_lshl_add_u64 v[24:25], v[212:213], 0, s[14:15]
	s_mov_b32 m0, s78
	s_nop 0
	global_load_lds_dwordx4 v[24:25], off
	v_lshl_add_u64 v[24:25], v[212:213], 0, s[16:17]
	s_mov_b32 m0, s79
	s_nop 0
	global_load_lds_dwordx4 v[24:25], off
	v_lshl_add_u64 v[24:25], v[214:215], 0, s[14:15]
	s_mov_b32 m0, s80
	s_nop 0
	global_load_lds_dwordx4 v[24:25], off
	v_lshl_add_u64 v[24:25], v[214:215], 0, s[16:17]
	s_mov_b32 m0, s81
	s_nop 0
	global_load_lds_dwordx4 v[24:25], off
